# v030 + first attention QK wait lgkmcnt(15) + the 27 flat stores issued as global stores
# speedup vs baseline: 1.0034x; 1.0007x over previous
; DI float bf1(const bf16_t* p) { return __uint_as_float((unsigned)(*(GAS const bf16_t*)p) << 16); }
; DI int obid() { int b = blockIdx.x; asm volatile("" : "+s"(b)); return b; }
; DI void phase_scan1(const bf16_t* A, const bf16_t* U, float* agg) {
;     ...
;     for (int it = obid(); it < 256; it += gridDim.x) {
;         const int b = it >> 4, c = it & 15; const size_t base = ((size_t)b * TT + (size_t)c * 257) * 512 + ch;
;         float Pl = 0.f, S = 0.f;
;         for (int s0 = 0; s0 < 256; s0 += 8) {
;             float a[8], u[8];
; #pragma unroll
;             for (int e = 0; e < 8; ++e) { a[e] = bf1(A + base + (size_t)(s0 + e) * 512); u[e] = bf1(U + base + (size_t)(s0 + e) * 512); }
.LBB0_132:
	v_add_co_u32_e32 v8, vcc, 0xf7f7f000, v6
	global_load_ushort v14, v[6:7], off offset:-4096
	global_load_ushort v15, v[6:7], off offset:-3072
	global_load_ushort v16, v[6:7], off offset:-2048
	global_load_ushort v17, v[6:7], off offset:-1024
	global_load_ushort v18, v[6:7], off
	v_addc_co_u32_e32 v9, vcc, -1, v7, vcc
	v_add_co_u32_e32 v10, vcc, 0xfffff000, v6
	s_add_i32 s7, s7, 8
	s_nop 0
	v_addc_co_u32_e32 v11, vcc, -1, v7, vcc
	v_add_co_u32_e32 v12, vcc, 0xf7f80000, v6
	s_waitcnt lgkmcnt(0)
	global_load_ushort v19, v[8:9], off offset:-3072
	global_load_ushort v20, v[8:9], off offset:-1024
	global_load_ushort v21, v[10:11], off offset:-3072
	global_load_ushort v22, v[10:11], off offset:-2048
	s_nop 0
	global_load_ushort v11, v[10:11], off offset:-1024
	v_addc_co_u32_e32 v13, vcc, -1, v7, vcc
	global_load_ushort v23, v[12:13], off offset:-3072
	global_load_ushort v24, v[12:13], off offset:-1024
	global_load_ushort v25, v[8:9], off
	s_nop 0
	global_load_ushort v9, v[8:9], off offset:-2048
	s_nop 0
	global_load_ushort v26, v[12:13], off
	s_nop 0
	global_load_ushort v13, v[12:13], off offset:-2048
	s_cmpk_lt_u32 s7, 0xf8
	v_lshl_add_u64 v[6:7], v[6:7], 0, s[74:75]
	v_add_co_u32_e32 v40, vcc, 0xf7f7f000, v6
	global_load_ushort v46, v[6:7], off offset:-4096
	global_load_ushort v47, v[6:7], off offset:-3072
	global_load_ushort v48, v[6:7], off offset:-2048
	global_load_ushort v49, v[6:7], off offset:-1024
	global_load_ushort v50, v[6:7], off
	v_addc_co_u32_e32 v41, vcc, -1, v7, vcc
	v_add_co_u32_e32 v42, vcc, 0xfffff000, v6
	s_add_i32 s7, s7, 8
	s_nop 0
	v_addc_co_u32_e32 v43, vcc, -1, v7, vcc
	v_add_co_u32_e32 v44, vcc, 0xf7f80000, v6
	s_waitcnt lgkmcnt(0)
	global_load_ushort v51, v[40:41], off offset:-3072
	global_load_ushort v52, v[40:41], off offset:-1024
	global_load_ushort v53, v[42:43], off offset:-3072
	global_load_ushort v54, v[42:43], off offset:-2048
	s_nop 0
	global_load_ushort v43, v[42:43], off offset:-1024
	v_addc_co_u32_e32 v45, vcc, -1, v7, vcc
	global_load_ushort v55, v[44:45], off offset:-3072
	global_load_ushort v56, v[44:45], off offset:-1024
	global_load_ushort v57, v[40:41], off
	s_nop 0
	global_load_ushort v41, v[40:41], off offset:-2048
	s_nop 0
	global_load_ushort v58, v[44:45], off
	s_nop 0
	global_load_ushort v45, v[44:45], off offset:-2048
	s_cmpk_lt_u32 s7, 0xf8
	v_lshl_add_u64 v[6:7], v[6:7], 0, s[74:75]
	v_add_co_u32_e32 v72, vcc, 0xf7f7f000, v6
	global_load_ushort v78, v[6:7], off offset:-4096
	global_load_ushort v79, v[6:7], off offset:-3072
	global_load_ushort v80, v[6:7], off offset:-2048
	global_load_ushort v81, v[6:7], off offset:-1024
	global_load_ushort v82, v[6:7], off
	v_addc_co_u32_e32 v73, vcc, -1, v7, vcc
	v_add_co_u32_e32 v74, vcc, 0xfffff000, v6
	s_add_i32 s7, s7, 8
	s_nop 0
	v_addc_co_u32_e32 v75, vcc, -1, v7, vcc
	v_add_co_u32_e32 v76, vcc, 0xf7f80000, v6
	s_waitcnt lgkmcnt(0)
	global_load_ushort v83, v[72:73], off offset:-3072
	global_load_ushort v84, v[72:73], off offset:-1024
	global_load_ushort v85, v[74:75], off offset:-3072
	global_load_ushort v86, v[74:75], off offset:-2048
	s_nop 0
	global_load_ushort v75, v[74:75], off offset:-1024
	v_addc_co_u32_e32 v77, vcc, -1, v7, vcc
	global_load_ushort v87, v[76:77], off offset:-3072
	global_load_ushort v88, v[76:77], off offset:-1024
	global_load_ushort v89, v[72:73], off
	s_nop 0
	global_load_ushort v73, v[72:73], off offset:-2048
	s_nop 0
	global_load_ushort v90, v[76:77], off
	s_nop 0
	global_load_ushort v77, v[76:77], off offset:-2048
	s_cmpk_lt_u32 s7, 0xf8
	v_lshl_add_u64 v[6:7], v[6:7], 0, s[74:75]
	v_add_co_u32_e32 v104, vcc, 0xf7f7f000, v6
	global_load_ushort v110, v[6:7], off offset:-4096
	global_load_ushort v111, v[6:7], off offset:-3072
	global_load_ushort v112, v[6:7], off offset:-2048
	global_load_ushort v113, v[6:7], off offset:-1024
	global_load_ushort v114, v[6:7], off
	v_addc_co_u32_e32 v105, vcc, -1, v7, vcc
	v_add_co_u32_e32 v106, vcc, 0xfffff000, v6
	s_add_i32 s7, s7, 8
	s_nop 0
	v_addc_co_u32_e32 v107, vcc, -1, v7, vcc
	v_add_co_u32_e32 v108, vcc, 0xf7f80000, v6
	s_waitcnt lgkmcnt(0)
	global_load_ushort v115, v[104:105], off offset:-3072
	global_load_ushort v116, v[104:105], off offset:-1024
	global_load_ushort v117, v[106:107], off offset:-3072
	global_load_ushort v118, v[106:107], off offset:-2048
	s_nop 0
	global_load_ushort v107, v[106:107], off offset:-1024
	v_addc_co_u32_e32 v109, vcc, -1, v7, vcc
	global_load_ushort v119, v[108:109], off offset:-3072
	global_load_ushort v120, v[108:109], off offset:-1024
	global_load_ushort v121, v[104:105], off
	s_nop 0
	global_load_ushort v105, v[104:105], off offset:-2048
	s_nop 0
	global_load_ushort v122, v[108:109], off
	s_nop 0
	global_load_ushort v109, v[108:109], off offset:-2048
	s_cmpk_lt_u32 s7, 0xf8
	v_lshl_add_u64 v[6:7], v[6:7], 0, s[74:75]
	s_waitcnt vmcnt(48)
; DI float bf1(const bf16_t* p) { return __uint_as_float((unsigned)(*(GAS const bf16_t*)p) << 16); }
; DI void phase_scan1(const bf16_t* A, const bf16_t* U, float* agg) {
;     ...
;         for (int s0 = 0; s0 < 256; s0 += 8) {
;             float a[8], u[8];
; #pragma unroll
;             for (int e = 0; e < 8; ++e) { a[e] = bf1(A + base + (size_t)(s0 + e) * 512); u[e] = bf1(U + base + (size_t)(s0 + e) * 512); }
; #pragma unroll
;             for (int e = 0; e < 8; ++e) { S = __expf(a[e]) * S + u[e]; Pl += a[e]; }
;         }
	v_lshlrev_b32_e32 v27, 16, v14
	v_lshlrev_b32_e32 v8, 16, v15
	v_lshlrev_b32_e32 v10, 16, v16
	v_lshlrev_b32_e32 v12, 16, v17
	v_lshlrev_b32_e32 v14, 16, v18
	v_lshlrev_b32_e32 v15, 16, v19
	v_lshlrev_b32_e32 v17, 16, v20
	v_lshlrev_b32_e32 v19, 16, v23
	v_add_f32_e32 v5, v5, v15
	v_lshlrev_b32_e32 v29, 16, v11
	v_mul_f32_e32 v11, 0x3fb8aa3b, v15
	v_lshlrev_b32_e32 v9, 16, v9
	v_exp_f32_e32 v23, v11
	v_mul_f32_e32 v20, 0x3fb8aa3b, v9
	v_mul_f32_e32 v15, 0x3fb8aa3b, v17
	v_lshlrev_b32_e32 v11, 16, v25
	v_exp_f32_e32 v32, v20
	v_lshlrev_b32_e32 v28, 16, v21
	v_lshlrev_b32_e32 v21, 16, v24
	v_exp_f32_e32 v24, v15
	v_mul_f32_e32 v25, 0x3fb8aa3b, v11
	v_mul_f32_e32 v16, 0x3fb8aa3b, v19
	v_exp_f32_e32 v25, v25
	v_lshlrev_b32_e32 v22, 16, v22
	v_lshlrev_b32_e32 v13, 16, v13
	v_exp_f32_e32 v31, v16
	v_fmac_f32_e32 v28, v4, v23
	v_lshlrev_b32_e32 v15, 16, v26
	v_mul_f32_e32 v26, 0x3fb8aa3b, v13
	v_fmac_f32_e32 v22, v28, v32
	v_exp_f32_e32 v16, v26
	v_fmac_f32_e32 v29, v22, v24
	v_fmac_f32_e32 v27, v29, v25
	v_mul_f32_e32 v18, 0x3fb8aa3b, v21
	v_mul_f32_e32 v4, v27, v31
	v_exp_f32_e32 v18, v18
	v_pk_add_f32 v[4:5], v[4:5], v[8:9]
	v_mul_f32_e32 v30, 0x3fb8aa3b, v15
	v_pk_mul_f32 v[8:9], v[4:5], v[16:17]
	v_pk_add_f32 v[4:5], v[4:5], v[16:17]
	v_exp_f32_e32 v20, v30
	v_mov_b32_e32 v9, v5
	v_pk_add_f32 v[4:5], v[8:9], v[10:11]
	s_nop 0
	v_pk_mul_f32 v[8:9], v[4:5], v[18:19]
	v_pk_add_f32 v[4:5], v[4:5], v[18:19]
	s_nop 0
	v_mov_b32_e32 v9, v5
	v_pk_add_f32 v[4:5], v[8:9], v[12:13]
	s_nop 0
	v_pk_mul_f32 v[8:9], v[4:5], v[20:21]
	v_pk_add_f32 v[4:5], v[4:5], v[20:21]
	s_nop 0
	v_mov_b32_e32 v9, v5
	v_pk_add_f32 v[4:5], v[8:9], v[14:15]
	s_waitcnt vmcnt(32)
	v_lshlrev_b32_e32 v27, 16, v46
	v_lshlrev_b32_e32 v8, 16, v47
	v_lshlrev_b32_e32 v10, 16, v48
	v_lshlrev_b32_e32 v12, 16, v49
	v_lshlrev_b32_e32 v14, 16, v50
	v_lshlrev_b32_e32 v15, 16, v51
	v_lshlrev_b32_e32 v17, 16, v52
	v_lshlrev_b32_e32 v19, 16, v55
	v_add_f32_e32 v5, v5, v15
	v_lshlrev_b32_e32 v29, 16, v43
	v_mul_f32_e32 v11, 0x3fb8aa3b, v15
	v_lshlrev_b32_e32 v9, 16, v41
	v_exp_f32_e32 v23, v11
	v_mul_f32_e32 v20, 0x3fb8aa3b, v9
	v_mul_f32_e32 v15, 0x3fb8aa3b, v17
	v_lshlrev_b32_e32 v11, 16, v57
	v_exp_f32_e32 v32, v20
	v_lshlrev_b32_e32 v28, 16, v53
	v_lshlrev_b32_e32 v21, 16, v56
	v_exp_f32_e32 v24, v15
	v_mul_f32_e32 v25, 0x3fb8aa3b, v11
	v_mul_f32_e32 v16, 0x3fb8aa3b, v19
	v_exp_f32_e32 v25, v25
	v_lshlrev_b32_e32 v22, 16, v54
	v_lshlrev_b32_e32 v13, 16, v45
	v_exp_f32_e32 v31, v16
	v_fmac_f32_e32 v28, v4, v23
	v_lshlrev_b32_e32 v15, 16, v58
	v_mul_f32_e32 v26, 0x3fb8aa3b, v13
	v_fmac_f32_e32 v22, v28, v32
	v_exp_f32_e32 v16, v26
	v_fmac_f32_e32 v29, v22, v24
	v_fmac_f32_e32 v27, v29, v25
	v_mul_f32_e32 v18, 0x3fb8aa3b, v21
	v_mul_f32_e32 v4, v27, v31
	v_exp_f32_e32 v18, v18
	v_pk_add_f32 v[4:5], v[4:5], v[8:9]
	v_mul_f32_e32 v30, 0x3fb8aa3b, v15
	v_pk_mul_f32 v[8:9], v[4:5], v[16:17]
	v_pk_add_f32 v[4:5], v[4:5], v[16:17]
	v_exp_f32_e32 v20, v30
	v_mov_b32_e32 v9, v5
	v_pk_add_f32 v[4:5], v[8:9], v[10:11]
	s_nop 0
	v_pk_mul_f32 v[8:9], v[4:5], v[18:19]
	v_pk_add_f32 v[4:5], v[4:5], v[18:19]
	s_nop 0
	v_mov_b32_e32 v9, v5
	v_pk_add_f32 v[4:5], v[8:9], v[12:13]
	s_nop 0
	v_pk_mul_f32 v[8:9], v[4:5], v[20:21]
	v_pk_add_f32 v[4:5], v[4:5], v[20:21]
	s_nop 0
	v_mov_b32_e32 v9, v5
	v_pk_add_f32 v[4:5], v[8:9], v[14:15]
	s_waitcnt vmcnt(16)
	v_lshlrev_b32_e32 v27, 16, v78
	v_lshlrev_b32_e32 v8, 16, v79
	v_lshlrev_b32_e32 v10, 16, v80
	v_lshlrev_b32_e32 v12, 16, v81
	v_lshlrev_b32_e32 v14, 16, v82
	v_lshlrev_b32_e32 v15, 16, v83
	v_lshlrev_b32_e32 v17, 16, v84
	v_lshlrev_b32_e32 v19, 16, v87
	v_add_f32_e32 v5, v5, v15
	v_lshlrev_b32_e32 v29, 16, v75
	v_mul_f32_e32 v11, 0x3fb8aa3b, v15
	v_lshlrev_b32_e32 v9, 16, v73
	v_exp_f32_e32 v23, v11
	v_mul_f32_e32 v20, 0x3fb8aa3b, v9
	v_mul_f32_e32 v15, 0x3fb8aa3b, v17
	v_lshlrev_b32_e32 v11, 16, v89
	v_exp_f32_e32 v32, v20
	v_lshlrev_b32_e32 v28, 16, v85
	v_lshlrev_b32_e32 v21, 16, v88
	v_exp_f32_e32 v24, v15
	v_mul_f32_e32 v25, 0x3fb8aa3b, v11
	v_mul_f32_e32 v16, 0x3fb8aa3b, v19
	v_exp_f32_e32 v25, v25
	v_lshlrev_b32_e32 v22, 16, v86
	v_lshlrev_b32_e32 v13, 16, v77
	v_exp_f32_e32 v31, v16
	v_fmac_f32_e32 v28, v4, v23
	v_lshlrev_b32_e32 v15, 16, v90
	v_mul_f32_e32 v26, 0x3fb8aa3b, v13
	v_fmac_f32_e32 v22, v28, v32
	v_exp_f32_e32 v16, v26
	v_fmac_f32_e32 v29, v22, v24
	v_fmac_f32_e32 v27, v29, v25
	v_mul_f32_e32 v18, 0x3fb8aa3b, v21
	v_mul_f32_e32 v4, v27, v31
	v_exp_f32_e32 v18, v18
	v_pk_add_f32 v[4:5], v[4:5], v[8:9]
	v_mul_f32_e32 v30, 0x3fb8aa3b, v15
	v_pk_mul_f32 v[8:9], v[4:5], v[16:17]
	v_pk_add_f32 v[4:5], v[4:5], v[16:17]
	v_exp_f32_e32 v20, v30
	v_mov_b32_e32 v9, v5
	v_pk_add_f32 v[4:5], v[8:9], v[10:11]
	s_nop 0
	v_pk_mul_f32 v[8:9], v[4:5], v[18:19]
	v_pk_add_f32 v[4:5], v[4:5], v[18:19]
	s_nop 0
	v_mov_b32_e32 v9, v5
	v_pk_add_f32 v[4:5], v[8:9], v[12:13]
	s_nop 0
	v_pk_mul_f32 v[8:9], v[4:5], v[20:21]
	v_pk_add_f32 v[4:5], v[4:5], v[20:21]
	s_nop 0
	v_mov_b32_e32 v9, v5
	v_pk_add_f32 v[4:5], v[8:9], v[14:15]
	s_waitcnt vmcnt(0)
	v_lshlrev_b32_e32 v27, 16, v110
	v_lshlrev_b32_e32 v8, 16, v111
	v_lshlrev_b32_e32 v10, 16, v112
	v_lshlrev_b32_e32 v12, 16, v113
	v_lshlrev_b32_e32 v14, 16, v114
	v_lshlrev_b32_e32 v15, 16, v115
	v_lshlrev_b32_e32 v17, 16, v116
	v_lshlrev_b32_e32 v19, 16, v119
	v_add_f32_e32 v5, v5, v15
	v_lshlrev_b32_e32 v29, 16, v107
	v_mul_f32_e32 v11, 0x3fb8aa3b, v15
	v_lshlrev_b32_e32 v9, 16, v105
	v_exp_f32_e32 v23, v11
	v_mul_f32_e32 v20, 0x3fb8aa3b, v9
	v_mul_f32_e32 v15, 0x3fb8aa3b, v17
	v_lshlrev_b32_e32 v11, 16, v121
	v_exp_f32_e32 v32, v20
	v_lshlrev_b32_e32 v28, 16, v117
	v_lshlrev_b32_e32 v21, 16, v120
	v_exp_f32_e32 v24, v15
	v_mul_f32_e32 v25, 0x3fb8aa3b, v11
	v_mul_f32_e32 v16, 0x3fb8aa3b, v19
	v_exp_f32_e32 v25, v25
	v_lshlrev_b32_e32 v22, 16, v118
	v_lshlrev_b32_e32 v13, 16, v109
	v_exp_f32_e32 v31, v16
	v_fmac_f32_e32 v28, v4, v23
	v_lshlrev_b32_e32 v15, 16, v122
	v_mul_f32_e32 v26, 0x3fb8aa3b, v13
	v_fmac_f32_e32 v22, v28, v32
	v_exp_f32_e32 v16, v26
	v_fmac_f32_e32 v29, v22, v24
	v_fmac_f32_e32 v27, v29, v25
	v_mul_f32_e32 v18, 0x3fb8aa3b, v21
	v_mul_f32_e32 v4, v27, v31
	v_exp_f32_e32 v18, v18
	v_pk_add_f32 v[4:5], v[4:5], v[8:9]
	v_mul_f32_e32 v30, 0x3fb8aa3b, v15
	v_pk_mul_f32 v[8:9], v[4:5], v[16:17]
	v_pk_add_f32 v[4:5], v[4:5], v[16:17]
	v_exp_f32_e32 v20, v30
	v_mov_b32_e32 v9, v5
	v_pk_add_f32 v[4:5], v[8:9], v[10:11]
	s_nop 0
	v_pk_mul_f32 v[8:9], v[4:5], v[18:19]
	v_pk_add_f32 v[4:5], v[4:5], v[18:19]
	s_nop 0
	v_mov_b32_e32 v9, v5
	v_pk_add_f32 v[4:5], v[8:9], v[12:13]
	s_nop 0
	v_pk_mul_f32 v[8:9], v[4:5], v[20:21]
	v_pk_add_f32 v[4:5], v[4:5], v[20:21]
	s_nop 0
	v_mov_b32_e32 v9, v5
	v_pk_add_f32 v[4:5], v[8:9], v[14:15]
	s_cbranch_scc1 .LBB0_132
; DI float bf1(const bf16_t* p) { return __uint_as_float((unsigned)(*(GAS const bf16_t*)p) << 16); }
; DI int obid() { int b = blockIdx.x; asm volatile("" : "+s"(b)); return b; }
; DI void phase_scan1(const bf16_t* A, const bf16_t* U, float* agg) {
;     ...
;     for (int it = obid(); it < 256; it += gridDim.x) {
;         const int b = it >> 4, c = it & 15; const size_t base = ((size_t)b * TT + (size_t)c * 257) * 512 + ch;
;         float Pl = 0.f, S = 0.f;
;         for (int s0 = 0; s0 < 256; s0 += 8) {
;             float a[8], u[8];
; #pragma unroll
;             for (int e = 0; e < 8; ++e) { a[e] = bf1(A + base + (size_t)(s0 + e) * 512); u[e] = bf1(U + base + (size_t)(s0 + e) * 512); }
; #pragma unroll
;             for (int e = 0; e < 8; ++e) { S = __expf(a[e]) * S + u[e]; Pl += a[e]; }
;         }
;         { const float a = bf1(A + base + (size_t)256 * 512), u = bf1(U + base + (size_t)256 * 512); S = __expf(a) * S + u; Pl += a; }
;         agg[((size_t)it * 512 + ch) * 2] = __expf(Pl); agg[((size_t)it * 512 + ch) * 2 + 1] = S;
	s_and_b32 s7, s4, 15
	s_mul_hi_i32 s9, s5, 0x1010
	s_mulk_i32 s5, 0x1010
	s_mulk_i32 s7, 0x101
	s_add_u32 s8, s5, s7
	s_addc_u32 s9, s9, 0
	s_lshl_b64 s[8:9], s[8:9], 9
	v_lshl_add_u64 v[6:7], s[8:9], 0, v[0:1]
	v_lshlrev_b64 v[6:7], 1, v[6:7]
	v_lshl_add_u64 v[8:9], s[28:29], 0, v[6:7]
	s_mov_b32 s5, 0x40000
	v_add_co_u32_e32 v8, vcc, s5, v8
	v_lshl_add_u64 v[6:7], s[38:39], 0, v[6:7]
	s_nop 0
	v_addc_co_u32_e32 v9, vcc, 0, v9, vcc
	global_load_ushort v8, v[8:9], off
	v_add_co_u32_e32 v6, vcc, s5, v6
	s_ashr_i32 s5, s4, 31
	s_nop 0
	v_addc_co_u32_e32 v7, vcc, 0, v7, vcc
	global_load_ushort v9, v[6:7], off
	s_add_i32 s6, s6, s62
	s_lshl_b64 s[8:9], s[4:5], 12
	s_add_i32 s4, s4, s62
	v_lshl_add_u64 v[6:7], v[2:3], 0, s[8:9]
	s_cmpk_gt_i32 s4, 0xff
	s_waitcnt vmcnt(1)
	v_lshlrev_b32_e32 v8, 16, v8
	v_mul_f32_e32 v10, 0x3fb8aa3b, v8
	v_add_f32_e32 v5, v5, v8
	v_exp_f32_e32 v10, v10
	v_mul_f32_e32 v5, 0x3fb8aa3b, v5
	v_exp_f32_e32 v8, v5
	s_waitcnt vmcnt(0)
	v_lshlrev_b32_e32 v9, 16, v9
	v_fmac_f32_e32 v9, v4, v10
	global_store_dwordx2 v[6:7], v[8:9], off
	s_cbranch_scc0 .LBB0_131
